# baseline (speedup 1.0000x reference)
; __device__ __forceinline__ unsigned xb_ld(unsigned* p)              { return __hip_atomic_load(p, __ATOMIC_RELAXED, __HIP_MEMORY_SCOPE_AGENT); }
; __device__ __forceinline__ unsigned xb_add(unsigned* p, unsigned v) { return __hip_atomic_fetch_add(p, v, __ATOMIC_RELAXED, __HIP_MEMORY_SCOPE_AGENT); }
; #define XB_SPIN(cond, bar) do { unsigned _sp = 0; while (cond) { __builtin_amdgcn_s_sleep(1); \
;     if ((++_sp & 255u) == 0u) { if (xb_ld(&(bar)[XB_TMO])) break; if (_sp > XB_SPIN_CAP) { atomicAdd(&(bar)[XB_TMO], 1u); break; } } } } while (0)
; __device__ __forceinline__ void xcd_barrier(const XcdBarrier& b) {
;     ...
;         const unsigned old = xb_add(&bar[XB_XSUB(b.x)], 1u);
;         const unsigned gen = old / nloc;
;         if (old + 1u == (gen + 1u) * nloc) {
;             __builtin_amdgcn_fence(__ATOMIC_RELEASE, "agent");
;             asm volatile("s_waitcnt vmcnt(0)" ::: "memory");
;             const unsigned og = xb_add(&bar[XB_TOP], 1u);
;             const unsigned tg = og / nx;
;             if (og + 1u == (tg + 1u) * nx) xb_add(&bar[XB_TOPGEN], 1u);
;             else XB_SPIN(xb_ld(&bar[XB_TOPGEN]) == tg, bar);
.Llb_go_5:
	s_add_u32 s22, s14, 0x25d06000
	s_addc_u32 s23, s15, 0
	v_mov_b32_e32 v2, 0
	v_mov_b32_e32 v3, 1
	s_and_b32 s16, s2, 7
	s_lshl_b32 s16, s16, 8
	s_add_u32 s20, s14, 0x25d05000
	s_addc_u32 s21, s15, 0
	s_add_u32 s20, s20, s16
	s_addc_u32 s21, s21, 0
	v_mov_b32_e32 v2, 0
	v_mov_b32_e32 v3, 1
	global_atomic_add v4, v2, v3, s[20:21] sc0
	buffer_inv sc1
	global_atomic_add v2, v3, s[22:23]
	s_waitcnt vmcnt(2)
	v_readfirstlane_b32 s17, v4
	s_lshr_b32 s22, s17, 5
	s_add_u32 s17, s17, 1
	s_and_b32 s17, s17, 31
	s_cmp_eq_u32 s17, 0
	s_cbranch_scc0 .Llb_wait_5
	global_atomic_add v2, v3, s[20:21] offset:2048
	s_waitcnt vmcnt(2)
	s_branch .LBB0_865
